# XCD barrier: waiting workgroups poll the global generation word directly instead of waiting for their XCD leader to republish it (one hop less per barrier)
# speedup vs baseline: 1.0023x; 1.0023x over previous
; __device__ __forceinline__ unsigned xb_ld(unsigned* p)              { return __hip_atomic_load(p, __ATOMIC_RELAXED, __HIP_MEMORY_SCOPE_AGENT); }
; __device__ __forceinline__ unsigned xb_add(unsigned* p, unsigned v) { return __hip_atomic_fetch_add(p, v, __ATOMIC_RELAXED, __HIP_MEMORY_SCOPE_AGENT); }
; #define XB_SPIN(cond, bar) do { unsigned _sp = 0; while (cond) { __builtin_amdgcn_s_sleep(1); \
;     if ((++_sp & 255u) == 0u) { if (xb_ld(&(bar)[XB_TMO])) break; if (_sp > XB_SPIN_CAP) { atomicAdd(&(bar)[XB_TMO], 1u); break; } } } } while (0)
; __device__ __forceinline__ void xcd_barrier(const XcdBarrier& b) {
;     ...
;         const unsigned old = xb_add(&bar[XB_XSUB(b.x)], 1u);
;         const unsigned gen = old / nloc;
;         if (old + 1u == (gen + 1u) * nloc) {
;             __builtin_amdgcn_fence(__ATOMIC_RELEASE, "agent");
;             asm volatile("s_waitcnt vmcnt(0)" ::: "memory");
;             const unsigned og = xb_add(&bar[XB_TOP], 1u);
;             const unsigned tg = og / nx;
;             if (og + 1u == (tg + 1u) * nx) xb_add(&bar[XB_TOPGEN], 1u);
;             else XB_SPIN(xb_ld(&bar[XB_TOPGEN]) == tg, bar);
;             __builtin_amdgcn_fence(__ATOMIC_ACQUIRE, "agent");
;             xb_add(&bar[XB_XGEN(b.x)], 1u);
;             asm volatile("s_waitcnt vmcnt(0)" ::: "memory");
;         } else {
;             XB_SPIN(xb_ld(&bar[XB_XGEN(b.x)]) == gen, bar);
;             __builtin_amdgcn_fence(__ATOMIC_ACQUIRE, "agent");
;             asm volatile("s_waitcnt vmcnt(0)" ::: "memory");
;         }
.LBB0_129:
	s_or_b64 exec, exec, s[6:7]
	v_cvt_f32_u32_e32 v4, v2
	buffer_inv sc1
	s_waitcnt vmcnt(1)
	v_readfirstlane_b32 s2, v3
	v_sub_u32_e32 v3, 0, v2
	v_rcp_iflag_f32_e32 v4, v4
	v_add_u32_e32 v5, s2, v1
	v_mul_f32_e32 v4, 0x4f7ffffe, v4
	v_cvt_u32_f32_e32 v4, v4
	v_mul_lo_u32 v1, v3, v4
	v_mul_hi_u32 v1, v4, v1
	v_add_u32_e32 v1, v4, v1
	v_mul_hi_u32 v1, v5, v1
	v_mul_lo_u32 v3, v1, v2
	v_sub_u32_e32 v3, v5, v3
	v_add_u32_e32 v4, 1, v1
	v_cmp_ge_u32_e32 vcc, v3, v2
	s_nop 1
	v_cndmask_b32_e32 v1, v1, v4, vcc
	v_sub_u32_e32 v4, v3, v2
	v_cndmask_b32_e32 v3, v3, v4, vcc
	v_add_u32_e32 v4, 1, v1
	v_cmp_ge_u32_e32 vcc, v3, v2
	v_add_u32_e32 v3, 1, v5
	s_nop 0
	v_cndmask_b32_e32 v1, v1, v4, vcc
	v_mul_lo_u32 v4, v2, v1
	v_add_u32_e32 v2, v4, v2
	v_cmp_ne_u32_e32 vcc, v3, v2
	s_and_saveexec_b64 s[2:3], vcc
	s_xor_b64 s[6:7], exec, s[2:3]
	s_cbranch_execz .LBB0_143
	s_waitcnt lgkmcnt(0)
	s_add_u32 s12, s88, 0x1fa63500
	s_addc_u32 s13, s89, 0
	v_mov_b32_e32 v0, 0
	global_load_dword v0, v0, s[12:13] sc1
	s_waitcnt vmcnt(0)
	v_cmp_eq_u32_e32 vcc, v0, v1
	s_and_saveexec_b64 s[8:9], vcc
	s_cbranch_execz .LBB0_142
	s_add_u32 s10, s88, 0x1fa60200
	s_addc_u32 s11, s89, 0
	s_mov_b32 s2, 1
	s_mov_b64 s[14:15], 0
	v_mov_b32_e32 v0, 0
	s_branch .LBB0_133

; __device__ __forceinline__ unsigned xb_ld(unsigned* p)              { return __hip_atomic_load(p, __ATOMIC_RELAXED, __HIP_MEMORY_SCOPE_AGENT); }
; __device__ __forceinline__ unsigned xb_add(unsigned* p, unsigned v) { return __hip_atomic_fetch_add(p, v, __ATOMIC_RELAXED, __HIP_MEMORY_SCOPE_AGENT); }
; #define XB_SPIN(cond, bar) do { unsigned _sp = 0; while (cond) { __builtin_amdgcn_s_sleep(1); \
;     if ((++_sp & 255u) == 0u) { if (xb_ld(&(bar)[XB_TMO])) break; if (_sp > XB_SPIN_CAP) { atomicAdd(&(bar)[XB_TMO], 1u); break; } } } } while (0)
; __device__ __forceinline__ void xcd_barrier(const XcdBarrier& b) {
;     ...
;         const unsigned old = xb_add(&bar[XB_XSUB(b.x)], 1u);
;         const unsigned gen = old / nloc;
;         if (old + 1u == (gen + 1u) * nloc) {
;             __builtin_amdgcn_fence(__ATOMIC_RELEASE, "agent");
;             asm volatile("s_waitcnt vmcnt(0)" ::: "memory");
;             const unsigned og = xb_add(&bar[XB_TOP], 1u);
;             const unsigned tg = og / nx;
;             if (og + 1u == (tg + 1u) * nx) xb_add(&bar[XB_TOPGEN], 1u);
;             else XB_SPIN(xb_ld(&bar[XB_TOPGEN]) == tg, bar);
;             __builtin_amdgcn_fence(__ATOMIC_ACQUIRE, "agent");
;             xb_add(&bar[XB_XGEN(b.x)], 1u);
;             asm volatile("s_waitcnt vmcnt(0)" ::: "memory");
;         } else {
;             XB_SPIN(xb_ld(&bar[XB_XGEN(b.x)]) == gen, bar);
;             __builtin_amdgcn_fence(__ATOMIC_ACQUIRE, "agent");
;             asm volatile("s_waitcnt vmcnt(0)" ::: "memory");
;         }
.LBB0_299:
	s_or_b64 exec, exec, s[6:7]
	v_cvt_f32_u32_e32 v4, v2
	buffer_inv sc1
	s_waitcnt vmcnt(1)
	v_readfirstlane_b32 s2, v3
	v_sub_u32_e32 v3, 0, v2
	v_rcp_iflag_f32_e32 v4, v4
	v_add_u32_e32 v5, s2, v1
	v_mul_f32_e32 v4, 0x4f7ffffe, v4
	v_cvt_u32_f32_e32 v4, v4
	v_mul_lo_u32 v1, v3, v4
	v_mul_hi_u32 v1, v4, v1
	v_add_u32_e32 v1, v4, v1
	v_mul_hi_u32 v1, v5, v1
	v_mul_lo_u32 v3, v1, v2
	v_sub_u32_e32 v3, v5, v3
	v_add_u32_e32 v4, 1, v1
	v_cmp_ge_u32_e32 vcc, v3, v2
	s_nop 1
	v_cndmask_b32_e32 v1, v1, v4, vcc
	v_sub_u32_e32 v4, v3, v2
	v_cndmask_b32_e32 v3, v3, v4, vcc
	v_add_u32_e32 v4, 1, v1
	v_cmp_ge_u32_e32 vcc, v3, v2
	v_add_u32_e32 v3, 1, v5
	s_nop 0
	v_cndmask_b32_e32 v1, v1, v4, vcc
	v_mul_lo_u32 v4, v2, v1
	v_add_u32_e32 v2, v4, v2
	v_cmp_ne_u32_e32 vcc, v3, v2
	s_and_saveexec_b64 s[2:3], vcc
	s_xor_b64 s[6:7], exec, s[2:3]
	s_cbranch_execz .LBB0_313
	s_waitcnt lgkmcnt(0)
	s_add_u32 s12, s88, 0x1fa63500
	s_addc_u32 s13, s89, 0
	v_mov_b32_e32 v0, 0
	global_load_dword v0, v0, s[12:13] sc1
	s_waitcnt vmcnt(0)
	v_cmp_eq_u32_e32 vcc, v0, v1
	s_and_saveexec_b64 s[8:9], vcc
	s_cbranch_execz .LBB0_312
	s_add_u32 s10, s88, 0x1fa60200
	s_addc_u32 s11, s89, 0
	s_mov_b32 s2, 1
	s_mov_b64 s[24:25], 0
	v_mov_b32_e32 v0, 0
	s_branch .LBB0_303

; __device__ __forceinline__ unsigned xb_ld(unsigned* p)              { return __hip_atomic_load(p, __ATOMIC_RELAXED, __HIP_MEMORY_SCOPE_AGENT); }
; __device__ __forceinline__ unsigned xb_add(unsigned* p, unsigned v) { return __hip_atomic_fetch_add(p, v, __ATOMIC_RELAXED, __HIP_MEMORY_SCOPE_AGENT); }
; #define XB_SPIN(cond, bar) do { unsigned _sp = 0; while (cond) { __builtin_amdgcn_s_sleep(1); \
;     if ((++_sp & 255u) == 0u) { if (xb_ld(&(bar)[XB_TMO])) break; if (_sp > XB_SPIN_CAP) { atomicAdd(&(bar)[XB_TMO], 1u); break; } } } } while (0)
; __device__ __forceinline__ void xcd_barrier(const XcdBarrier& b) {
;     ...
;         const unsigned old = xb_add(&bar[XB_XSUB(b.x)], 1u);
;         const unsigned gen = old / nloc;
;         if (old + 1u == (gen + 1u) * nloc) {
;             __builtin_amdgcn_fence(__ATOMIC_RELEASE, "agent");
;             asm volatile("s_waitcnt vmcnt(0)" ::: "memory");
;             const unsigned og = xb_add(&bar[XB_TOP], 1u);
;             const unsigned tg = og / nx;
;             if (og + 1u == (tg + 1u) * nx) xb_add(&bar[XB_TOPGEN], 1u);
;             else XB_SPIN(xb_ld(&bar[XB_TOPGEN]) == tg, bar);
;             __builtin_amdgcn_fence(__ATOMIC_ACQUIRE, "agent");
;             xb_add(&bar[XB_XGEN(b.x)], 1u);
;             asm volatile("s_waitcnt vmcnt(0)" ::: "memory");
;         } else {
;             XB_SPIN(xb_ld(&bar[XB_XGEN(b.x)]) == gen, bar);
;             __builtin_amdgcn_fence(__ATOMIC_ACQUIRE, "agent");
;             asm volatile("s_waitcnt vmcnt(0)" ::: "memory");
;         }
.LBB0_630:
	s_or_b64 exec, exec, s[8:9]
	v_cvt_f32_u32_e32 v4, v2
	buffer_inv sc1
	s_waitcnt vmcnt(1)
	v_readfirstlane_b32 s2, v3
	v_sub_u32_e32 v3, 0, v2
	s_lshl_b32 s4, s22, 6
	v_rcp_iflag_f32_e32 v4, v4
	v_add_u32_e32 v5, s2, v1
	v_mul_f32_e32 v4, 0x4f7ffffe, v4
	v_cvt_u32_f32_e32 v4, v4
	v_mul_lo_u32 v1, v3, v4
	v_mul_hi_u32 v1, v4, v1
	v_add_u32_e32 v1, v4, v1
	v_mul_hi_u32 v1, v5, v1
	v_mul_lo_u32 v3, v1, v2
	v_sub_u32_e32 v3, v5, v3
	v_add_u32_e32 v4, 1, v1
	v_cmp_ge_u32_e32 vcc, v3, v2
	s_nop 1
	v_cndmask_b32_e32 v1, v1, v4, vcc
	v_sub_u32_e32 v4, v3, v2
	v_cndmask_b32_e32 v3, v3, v4, vcc
	v_add_u32_e32 v4, 1, v1
	v_cmp_ge_u32_e32 vcc, v3, v2
	v_add_u32_e32 v3, 1, v5
	s_nop 0
	v_cndmask_b32_e32 v1, v1, v4, vcc
	v_mul_lo_u32 v4, v2, v1
	v_add_u32_e32 v2, v4, v2
	v_cmp_ne_u32_e32 vcc, v3, v2
	s_and_saveexec_b64 s[2:3], vcc
	s_xor_b64 s[8:9], exec, s[2:3]
	s_cbranch_execz .LBB0_644
	s_waitcnt lgkmcnt(0)
	s_add_u32 s14, s88, 0x1fa63500
	s_addc_u32 s15, s89, 0
	v_mov_b32_e32 v0, 0
	global_load_dword v0, v0, s[14:15] sc1
	s_waitcnt vmcnt(0)
	v_cmp_eq_u32_e32 vcc, v0, v1
	s_and_saveexec_b64 s[10:11], vcc
	s_cbranch_execz .LBB0_643
	s_add_u32 s12, s88, 0x1fa60200
	s_addc_u32 s13, s89, 0
	s_mov_b32 s2, 1
	s_mov_b64 s[24:25], 0
	v_mov_b32_e32 v0, 0
	s_branch .LBB0_634

; __device__ __forceinline__ unsigned xb_ld(unsigned* p)              { return __hip_atomic_load(p, __ATOMIC_RELAXED, __HIP_MEMORY_SCOPE_AGENT); }
; __device__ __forceinline__ unsigned xb_add(unsigned* p, unsigned v) { return __hip_atomic_fetch_add(p, v, __ATOMIC_RELAXED, __HIP_MEMORY_SCOPE_AGENT); }
; #define XB_SPIN(cond, bar) do { unsigned _sp = 0; while (cond) { __builtin_amdgcn_s_sleep(1); \
;     if ((++_sp & 255u) == 0u) { if (xb_ld(&(bar)[XB_TMO])) break; if (_sp > XB_SPIN_CAP) { atomicAdd(&(bar)[XB_TMO], 1u); break; } } } } while (0)
; __device__ __forceinline__ void xcd_barrier(const XcdBarrier& b) {
;     ...
;         const unsigned old = xb_add(&bar[XB_XSUB(b.x)], 1u);
;         const unsigned gen = old / nloc;
;         if (old + 1u == (gen + 1u) * nloc) {
;             __builtin_amdgcn_fence(__ATOMIC_RELEASE, "agent");
;             asm volatile("s_waitcnt vmcnt(0)" ::: "memory");
;             const unsigned og = xb_add(&bar[XB_TOP], 1u);
;             const unsigned tg = og / nx;
;             if (og + 1u == (tg + 1u) * nx) xb_add(&bar[XB_TOPGEN], 1u);
;             else XB_SPIN(xb_ld(&bar[XB_TOPGEN]) == tg, bar);
;             __builtin_amdgcn_fence(__ATOMIC_ACQUIRE, "agent");
;             xb_add(&bar[XB_XGEN(b.x)], 1u);
;             asm volatile("s_waitcnt vmcnt(0)" ::: "memory");
;         } else {
;             XB_SPIN(xb_ld(&bar[XB_XGEN(b.x)]) == gen, bar);
;             __builtin_amdgcn_fence(__ATOMIC_ACQUIRE, "agent");
;             asm volatile("s_waitcnt vmcnt(0)" ::: "memory");
;         }
.LBB0_930:
	global_atomic_add v4, v[172:173], v202, off sc0
	v_cvt_f32_u32_e32 v0, v3
	v_sub_u32_e32 v5, 0, v3
	v_rcp_iflag_f32_e32 v0, v0
	s_nop 0
	v_mul_f32_e32 v0, 0x4f7ffffe, v0
	v_cvt_u32_f32_e32 v0, v0
	v_mul_lo_u32 v5, v5, v0
	v_mul_hi_u32 v5, v0, v5
	v_add_u32_e32 v0, v0, v5
	buffer_inv sc1
	s_waitcnt vmcnt(1)
	v_mul_hi_u32 v0, v4, v0
	v_mul_lo_u32 v5, v0, v3
	v_sub_u32_e32 v5, v4, v5
	v_add_u32_e32 v6, 1, v0
	v_cmp_ge_u32_e32 vcc, v5, v3
	v_add_u32_e32 v4, 1, v4
	s_nop 0
	v_cndmask_b32_e32 v0, v0, v6, vcc
	v_sub_u32_e32 v6, v5, v3
	v_cndmask_b32_e32 v5, v5, v6, vcc
	v_add_u32_e32 v6, 1, v0
	v_cmp_ge_u32_e32 vcc, v5, v3
	s_nop 1
	v_cndmask_b32_e32 v0, v0, v6, vcc
	v_mul_lo_u32 v5, v3, v0
	v_add_u32_e32 v3, v5, v3
	v_cmp_ne_u32_e32 vcc, v4, v3
	s_and_saveexec_b64 s[2:3], vcc
	s_xor_b64 s[24:25], exec, s[2:3]
	s_cbranch_execz .LBB0_944
	s_waitcnt lgkmcnt(0)
	v_readlane_b32 s40, v243, 50
	v_readlane_b32 s41, v243, 51
	v_mov_b32_e32 v245, 0
	s_nop 4
	global_load_dword v2, v245, s[40:41] sc1
	s_waitcnt vmcnt(0)
	v_cmp_eq_u32_e32 vcc, v2, v0
	s_and_saveexec_b64 s[26:27], vcc
	s_cbranch_execz .LBB0_943
	s_mov_b32 s2, 1
	s_mov_b64 s[28:29], 0
	s_branch .LBB0_934

; __device__ __forceinline__ unsigned xb_ld(unsigned* p)              { return __hip_atomic_load(p, __ATOMIC_RELAXED, __HIP_MEMORY_SCOPE_AGENT); }
; #define XB_SPIN(cond, bar) do { unsigned _sp = 0; while (cond) { __builtin_amdgcn_s_sleep(1); \
;     if ((++_sp & 255u) == 0u) { if (xb_ld(&(bar)[XB_TMO])) break; if (_sp > XB_SPIN_CAP) { atomicAdd(&(bar)[XB_TMO], 1u); break; } } } } while (0)
; __device__ __forceinline__ void xcd_barrier(const XcdBarrier& b) {
;     ...
;             XB_SPIN(xb_ld(&bar[XB_XGEN(b.x)]) == gen, bar);
.LBB0_936:
	global_load_dword v2, v245, s[40:41] sc1
	s_add_i32 s2, s2, 1
	s_mov_b64 s[36:37], -1
	s_waitcnt vmcnt(0)
	v_cmp_ne_u32_e32 vcc, v2, v0
	s_orn2_b64 s[34:35], vcc, exec
	s_branch .LBB0_933
